# ml_seq phase A: waves 0-3 run the deferred block-transform chains before staging (waves 4-7 stage meanwhile)
# baseline (speedup 1.0000x reference)
.LBB0_791:
	s_cmp_eq_u32 s30, 0
	s_cbranch_scc1 .Lmlq_chains_first_done
	s_cmp_eq_u64 s[6:7], 0
	s_cbranch_scc1 .Lmlq_chains_first_done
	s_and_b32 s24, s30, 1
	s_mul_i32 s25, s24, 0x8200
	s_mulk_i32 s24, 0x440
	v_add_u32_e32 v122, s25, v176
	v_add_u32_e32 v123, s24, v164
	v_cvt_pk_bf16_f32 v194, v66, v67
	v_cvt_pk_bf16_f32 v195, v68, v69
	v_mov_b32_e32 v196, v0
	v_mov_b32_e32 v197, v0
	v_cvt_pk_bf16_f32 v198, v62, v63
	v_cvt_pk_bf16_f32 v199, v64, v65
	v_mov_b32_e32 v200, v0
	v_mov_b32_e32 v201, v0
	v_cvt_pk_bf16_f32 v202, v74, v75
	v_cvt_pk_bf16_f32 v203, v76, v77
	v_mov_b32_e32 v204, v0
	v_mov_b32_e32 v205, v0
	v_cvt_pk_bf16_f32 v206, v58, v59
	v_cvt_pk_bf16_f32 v207, v60, v61
	v_mov_b32_e32 v208, v0
	v_mov_b32_e32 v209, v0
	v_cvt_pk_bf16_f32 v210, v54, v55
	v_cvt_pk_bf16_f32 v211, v56, v57
	v_mov_b32_e32 v212, v0
	v_mov_b32_e32 v213, v0
	v_cvt_pk_bf16_f32 v214, v70, v71
	v_cvt_pk_bf16_f32 v215, v72, v73
	v_mov_b32_e32 v216, v0
	v_mov_b32_e32 v217, v0
	v_cvt_pk_bf16_f32 v218, v82, v83
	v_cvt_pk_bf16_f32 v219, v84, v85
	v_mov_b32_e32 v220, v0
	v_mov_b32_e32 v221, v0
	v_cvt_pk_bf16_f32 v222, v86, v87
	v_cvt_pk_bf16_f32 v223, v88, v89
	v_mov_b32_e32 v224, v0
	v_mov_b32_e32 v225, v0
	v_cvt_pk_bf16_f32 v124, v78, v79
	v_cvt_pk_bf16_f32 v125, v80, v81
	v_mov_b32_e32 v126, v0
	v_mov_b32_e32 v127, v0
	v_cvt_pk_bf16_f32 v128, v94, v95
	v_cvt_pk_bf16_f32 v129, v96, v97
	v_mov_b32_e32 v130, v0
	v_mov_b32_e32 v131, v0
	v_cvt_pk_bf16_f32 v132, v98, v99
	v_cvt_pk_bf16_f32 v133, v100, v101
	v_mov_b32_e32 v134, v0
	v_mov_b32_e32 v135, v0
	v_cvt_pk_bf16_f32 v136, v90, v91
	v_cvt_pk_bf16_f32 v137, v92, v93
	v_mov_b32_e32 v138, v0
	v_mov_b32_e32 v139, v0
	v_mfma_f32_16x16x32_bf16 v[194:197], v[30:33], v[194:197], 0
	v_mfma_f32_16x16x32_bf16 v[198:201], v[30:33], v[198:201], 0
	v_mfma_f32_16x16x32_bf16 v[202:205], v[30:33], v[202:205], 0
	v_mfma_f32_16x16x32_bf16 v[206:209], v[42:45], v[206:209], 0
	v_mfma_f32_16x16x32_bf16 v[210:213], v[42:45], v[210:213], 0
	v_mfma_f32_16x16x32_bf16 v[214:217], v[42:45], v[214:217], 0
	v_mfma_f32_16x16x32_bf16 v[218:221], v[46:49], v[218:221], 0
	v_mfma_f32_16x16x32_bf16 v[222:225], v[46:49], v[222:225], 0
	v_mfma_f32_16x16x32_bf16 v[124:127], v[46:49], v[124:127], 0
	v_mfma_f32_16x16x32_bf16 v[128:131], v[50:53], v[128:131], 0
	v_mfma_f32_16x16x32_bf16 v[132:135], v[50:53], v[132:135], 0
	v_mfma_f32_16x16x32_bf16 v[136:139], v[50:53], v[136:139], 0
	v_cvt_pk_bf16_f32 v194, v194, v195
	v_cvt_pk_bf16_f32 v195, v196, v197
	ds_write_b64 v122, v[194:195]
	v_cvt_pk_bf16_f32 v198, v198, v199
	v_cvt_pk_bf16_f32 v199, v200, v201
	ds_write_b64 v122, v[198:199] offset:16640
	v_cvt_pk_bf16_f32 v202, v202, v203
	v_cvt_pk_bf16_f32 v203, v204, v205
	v_cvt_pk_bf16_f32 v206, v206, v207
	v_cvt_pk_bf16_f32 v207, v208, v209
	ds_write_b64 v122, v[206:207] offset:32
	v_cvt_pk_bf16_f32 v210, v210, v211
	v_cvt_pk_bf16_f32 v211, v212, v213
	ds_write_b64 v122, v[210:211] offset:16672
	v_cvt_pk_bf16_f32 v214, v214, v215
	v_cvt_pk_bf16_f32 v215, v216, v217
	v_cvt_pk_bf16_f32 v218, v218, v219
	v_cvt_pk_bf16_f32 v219, v220, v221
	ds_write_b64 v122, v[218:219] offset:64
	v_cvt_pk_bf16_f32 v222, v222, v223
	v_cvt_pk_bf16_f32 v223, v224, v225
	ds_write_b64 v122, v[222:223] offset:16704
	v_cvt_pk_bf16_f32 v124, v124, v125
	v_cvt_pk_bf16_f32 v125, v126, v127
	v_cvt_pk_bf16_f32 v128, v128, v129
	v_cvt_pk_bf16_f32 v129, v130, v131
	ds_write_b64 v122, v[128:129] offset:96
	v_cvt_pk_bf16_f32 v132, v132, v133
	v_cvt_pk_bf16_f32 v133, v134, v135
	ds_write_b64 v122, v[132:133] offset:16736
	v_cvt_pk_bf16_f32 v136, v136, v137
	v_cvt_pk_bf16_f32 v137, v138, v139
	s_and_saveexec_b64 s[24:25], s[8:9]
	ds_write_b64 v123, v[202:203]
	ds_write_b64 v123, v[214:215] offset:32
	ds_write_b64 v123, v[124:125] offset:64
	ds_write_b64 v123, v[136:137] offset:96
	s_or_b64 exec, exec, s[24:25]

.Lmlq_noearly:
	v_and_b32_e32 v119, 0xffff0000, v142
	v_lshlrev_b32_e32 v118, 16, v142
	v_lshlrev_b32_e32 v120, 16, v143
	s_waitcnt lgkmcnt(9)
	v_mul_f32_e32 v106, v106, v119
	v_fmac_f32_e32 v106, v102, v118
	v_and_b32_e32 v121, 0xffff0000, v143
	v_fmac_f32_e32 v106, v110, v120
	v_fmac_f32_e32 v106, v114, v121
	v_cvt_pk_bf16_f32 v102, v106, s0
	ds_write_b16 v165, v102
	v_mul_f32_e32 v102, v153, v106
	v_cvt_pk_bf16_f32 v102, v102, s0
	ds_write_b16 v166, v102
	v_mul_f32_e32 v102, v107, v119
	v_fmac_f32_e32 v102, v103, v118
	v_fmac_f32_e32 v102, v111, v120
	v_fmac_f32_e32 v102, v115, v121
	v_cvt_pk_bf16_f32 v103, v102, s0
	v_mul_f32_e32 v102, v153, v102
	v_cvt_pk_bf16_f32 v102, v102, s0
	ds_write_b16 v168, v102
	v_mul_f32_e32 v102, v108, v119
	v_fmac_f32_e32 v102, v104, v118
	v_fmac_f32_e32 v102, v112, v120
	v_fmac_f32_e32 v102, v116, v121
	ds_write_b16 v167, v103
	v_cvt_pk_bf16_f32 v103, v102, s0
	v_mul_f32_e32 v102, v153, v102
	v_cvt_pk_bf16_f32 v102, v102, s0
	ds_write_b16 v170, v102
	v_mul_f32_e32 v102, v109, v119
	v_fmac_f32_e32 v102, v105, v118
	v_fmac_f32_e32 v102, v113, v120
	v_fmac_f32_e32 v102, v117, v121
	ds_write_b16 v169, v103
	v_cvt_pk_bf16_f32 v103, v102, s0
	v_mul_f32_e32 v102, v153, v102
	v_cvt_pk_bf16_f32 v102, v102, s0
	ds_write_b16 v171, v103
	ds_write_b16 v172, v102
.Lmlq_nochains_t0:
	s_cmpk_eq_i32 s30, 0x7f
	s_cbranch_scc1 .Lmlq_nolate
	global_load_dword v153, v[228:229], off offset:256
	global_load_dwordx2 v[142:143], v[230:231], off
